# sample-row residual reduce (x + 8 split-K partials): 72 loads per row issued in 3 batches ahead of the previous batch's stores instead of 8 serial load-wait-store rounds; on top of v25
# speedup vs baseline: 1.0023x; 1.0023x over previous
; DI unsigned pk2(float lo, float hi) { f32x2_t v = {lo, hi}; bf16x2_t b = __builtin_convertvector(v, bf16x2_t); return __builtin_bit_cast(unsigned, b); }
; DI void p10_hn(const Args& a, int lane, int wave) {
;     ...
;         } else {
;             f32x4 v[8];
;             const float* xr = a.in[1] + (size_t)(row - MP) * 2048; const float* pr = (const float*)(a.ws + WS_PART1) + (size_t)(row - MP) * 2048;
; #pragma unroll
;             for (int i = 0; i < 8; ++i) { v[i] = ((const f32x4*)xr)[lane + 64 * i];
; #pragma unroll
;                 for (int k = 0; k < 8; ++k) v[i] += ((const f32x4*)(pr + (size_t)k * (MS * 2048)))[lane + 64 * i];
;                 ((f32x4*)(a.out + (size_t)row * 2048))[lane + 64 * i] = v[i];
;                 u32x2 w; w.x = pk2(v[i][0], v[i][1]); w.y = pk2(v[i][2], v[i][3]);
;                 *(u32x2*)(H16 + (size_t)row * 2048 + 4 * (lane + 64 * i)) = w;
;                 const float b0 = bflo(w.x), b1 = bfhi(w.x), b2 = bflo(w.y), b3 = bfhi(w.y);
;                 ss += b0 * b0 + b1 * b1 + b2 * b2 + b3 * b3; }
;         }
.LBB0_1143:
	s_cmpk_gt_i32 s0, 0x3fff
	s_mov_b64 s[16:17], -1
	s_cbranch_scc0 .LBB0_1145
	s_add_i32 s6, s0, 0xffffc000
	s_lshl_b64 s[16:17], s[6:7], 13
	s_add_u32 s22, s38, s16
	s_addc_u32 s23, s39, s17
	s_add_u32 s20, s11, s16
	s_addc_u32 s21, s24, s17
	s_mov_b32 s1, s7
	s_lshl_b64 s[16:17], s[0:1], 12
	s_add_u32 s16, s8, s16
	s_addc_u32 s17, s9, s17
	s_lshl_b64 s[18:19], s[0:1], 13
	s_add_u32 s18, s26, s18
	s_addc_u32 s19, s27, s19
	v_mov_b32_e32 v5, v1
	global_load_dwordx4 v[44:47], v0, s[22:23]
	global_load_dwordx4 v[80:83], v0, s[22:23] offset:1024
	global_load_dwordx4 v[116:119], v0, s[22:23] offset:2048
	s_mov_b64 s[98:99], s[20:21]
	global_load_dwordx4 v[48:51], v0, s[98:99]
	global_load_dwordx4 v[84:87], v0, s[98:99] offset:1024
	global_load_dwordx4 v[120:123], v0, s[98:99] offset:2048
	s_add_u32 s98, s20, 0x400000
	s_addc_u32 s99, s21, 0
	global_load_dwordx4 v[52:55], v0, s[98:99]
	global_load_dwordx4 v[88:91], v0, s[98:99] offset:1024
	global_load_dwordx4 v[124:127], v0, s[98:99] offset:2048
	s_add_u32 s98, s20, 0x800000
	s_addc_u32 s99, s21, 0
	global_load_dwordx4 v[56:59], v0, s[98:99]
	global_load_dwordx4 v[92:95], v0, s[98:99] offset:1024
	global_load_dwordx4 v[128:131], v0, s[98:99] offset:2048
	s_add_u32 s98, s20, 0xc00000
	s_addc_u32 s99, s21, 0
	global_load_dwordx4 v[60:63], v0, s[98:99]
	global_load_dwordx4 v[96:99], v0, s[98:99] offset:1024
	global_load_dwordx4 v[132:135], v0, s[98:99] offset:2048
	s_add_u32 s98, s20, 0x1000000
	s_addc_u32 s99, s21, 0
	global_load_dwordx4 v[64:67], v0, s[98:99]
	global_load_dwordx4 v[100:103], v0, s[98:99] offset:1024
	global_load_dwordx4 v[136:139], v0, s[98:99] offset:2048
	s_add_u32 s98, s20, 0x1400000
	s_addc_u32 s99, s21, 0
	global_load_dwordx4 v[68:71], v0, s[98:99]
	global_load_dwordx4 v[104:107], v0, s[98:99] offset:1024
	global_load_dwordx4 v[140:143], v0, s[98:99] offset:2048
	s_add_u32 s98, s20, 0x1800000
	s_addc_u32 s99, s21, 0
	global_load_dwordx4 v[72:75], v0, s[98:99]
	global_load_dwordx4 v[108:111], v0, s[98:99] offset:1024
	global_load_dwordx4 v[144:147], v0, s[98:99] offset:2048
	s_add_u32 s98, s20, 0x1c00000
	s_addc_u32 s99, s21, 0
	global_load_dwordx4 v[76:79], v0, s[98:99]
	global_load_dwordx4 v[112:115], v0, s[98:99] offset:1024
	global_load_dwordx4 v[154:157], v0, s[98:99] offset:2048
	s_waitcnt vmcnt(0)
	v_pk_add_f32 v[168:169], v[46:47], v[50:51]
	v_pk_add_f32 v[166:167], v[44:45], v[48:49]
	v_pk_add_f32 v[168:169], v[168:169], v[54:55]
	v_pk_add_f32 v[166:167], v[166:167], v[52:53]
	v_pk_add_f32 v[168:169], v[168:169], v[58:59]
	v_pk_add_f32 v[166:167], v[166:167], v[56:57]
	v_pk_add_f32 v[168:169], v[168:169], v[62:63]
	v_pk_add_f32 v[166:167], v[166:167], v[60:61]
	v_pk_add_f32 v[168:169], v[168:169], v[66:67]
	v_pk_add_f32 v[166:167], v[166:167], v[64:65]
	v_pk_add_f32 v[168:169], v[168:169], v[70:71]
	v_pk_add_f32 v[166:167], v[166:167], v[68:69]
	v_pk_add_f32 v[168:169], v[168:169], v[74:75]
	v_pk_add_f32 v[166:167], v[166:167], v[72:73]
	v_pk_add_f32 v[168:169], v[168:169], v[78:79]
	v_pk_add_f32 v[166:167], v[166:167], v[76:77]
	v_pk_add_f32 v[172:173], v[82:83], v[86:87]
	v_pk_add_f32 v[170:171], v[80:81], v[84:85]
	v_pk_add_f32 v[172:173], v[172:173], v[90:91]
	v_pk_add_f32 v[170:171], v[170:171], v[88:89]
	v_pk_add_f32 v[172:173], v[172:173], v[94:95]
	v_pk_add_f32 v[170:171], v[170:171], v[92:93]
	v_pk_add_f32 v[172:173], v[172:173], v[98:99]
	v_pk_add_f32 v[170:171], v[170:171], v[96:97]
	v_pk_add_f32 v[172:173], v[172:173], v[102:103]
	v_pk_add_f32 v[170:171], v[170:171], v[100:101]
	v_pk_add_f32 v[172:173], v[172:173], v[106:107]
	v_pk_add_f32 v[170:171], v[170:171], v[104:105]
	v_pk_add_f32 v[172:173], v[172:173], v[110:111]
	v_pk_add_f32 v[170:171], v[170:171], v[108:109]
	v_pk_add_f32 v[172:173], v[172:173], v[114:115]
	v_pk_add_f32 v[170:171], v[170:171], v[112:113]
	v_pk_add_f32 v[176:177], v[118:119], v[122:123]
	v_pk_add_f32 v[174:175], v[116:117], v[120:121]
	v_pk_add_f32 v[176:177], v[176:177], v[126:127]
	v_pk_add_f32 v[174:175], v[174:175], v[124:125]
	v_pk_add_f32 v[176:177], v[176:177], v[130:131]
	v_pk_add_f32 v[174:175], v[174:175], v[128:129]
	v_pk_add_f32 v[176:177], v[176:177], v[134:135]
	v_pk_add_f32 v[174:175], v[174:175], v[132:133]
	v_pk_add_f32 v[176:177], v[176:177], v[138:139]
	v_pk_add_f32 v[174:175], v[174:175], v[136:137]
	v_pk_add_f32 v[176:177], v[176:177], v[142:143]
	v_pk_add_f32 v[174:175], v[174:175], v[140:141]
	v_pk_add_f32 v[176:177], v[176:177], v[146:147]
	v_pk_add_f32 v[174:175], v[174:175], v[144:145]
	v_pk_add_f32 v[176:177], v[176:177], v[156:157]
	v_pk_add_f32 v[174:175], v[174:175], v[154:155]
	global_load_dwordx4 v[44:47], v0, s[22:23] offset:3072
	global_load_dwordx4 v[80:83], v4, s[22:23]
	global_load_dwordx4 v[116:119], v4, s[22:23] offset:1024
	s_mov_b64 s[98:99], s[20:21]
	global_load_dwordx4 v[48:51], v0, s[98:99] offset:3072
	global_load_dwordx4 v[84:87], v4, s[98:99]
	global_load_dwordx4 v[120:123], v4, s[98:99] offset:1024
	s_add_u32 s98, s20, 0x400000
	s_addc_u32 s99, s21, 0
	global_load_dwordx4 v[52:55], v0, s[98:99] offset:3072
	global_load_dwordx4 v[88:91], v4, s[98:99]
	global_load_dwordx4 v[124:127], v4, s[98:99] offset:1024
	s_add_u32 s98, s20, 0x800000
	s_addc_u32 s99, s21, 0
	global_load_dwordx4 v[56:59], v0, s[98:99] offset:3072
	global_load_dwordx4 v[92:95], v4, s[98:99]
	global_load_dwordx4 v[128:131], v4, s[98:99] offset:1024
	s_add_u32 s98, s20, 0xc00000
	s_addc_u32 s99, s21, 0
	global_load_dwordx4 v[60:63], v0, s[98:99] offset:3072
	global_load_dwordx4 v[96:99], v4, s[98:99]
	global_load_dwordx4 v[132:135], v4, s[98:99] offset:1024
	s_add_u32 s98, s20, 0x1000000
; DI unsigned pk2(float lo, float hi) { f32x2_t v = {lo, hi}; bf16x2_t b = __builtin_convertvector(v, bf16x2_t); return __builtin_bit_cast(unsigned, b); }
; DI void p10_hn(const Args& a, int lane, int wave) {
;     ...
;             for (int i = 0; i < 8; ++i) { v[i] = ((const f32x4*)xr)[lane + 64 * i];
; #pragma unroll
;                 for (int k = 0; k < 8; ++k) v[i] += ((const f32x4*)(pr + (size_t)k * (MS * 2048)))[lane + 64 * i];
;                 ((f32x4*)(a.out + (size_t)row * 2048))[lane + 64 * i] = v[i];
;                 u32x2 w; w.x = pk2(v[i][0], v[i][1]); w.y = pk2(v[i][2], v[i][3]);
;                 *(u32x2*)(H16 + (size_t)row * 2048 + 4 * (lane + 64 * i)) = w;
;                 const float b0 = bflo(w.x), b1 = bfhi(w.x), b2 = bflo(w.y), b3 = bfhi(w.y);
;                 ss += b0 * b0 + b1 * b1 + b2 * b2 + b3 * b3; }
;         }
	s_addc_u32 s99, s21, 0
	global_load_dwordx4 v[64:67], v0, s[98:99] offset:3072
	global_load_dwordx4 v[100:103], v4, s[98:99]
	global_load_dwordx4 v[136:139], v4, s[98:99] offset:1024
	s_add_u32 s98, s20, 0x1400000
	s_addc_u32 s99, s21, 0
	global_load_dwordx4 v[68:71], v0, s[98:99] offset:3072
	global_load_dwordx4 v[104:107], v4, s[98:99]
	global_load_dwordx4 v[140:143], v4, s[98:99] offset:1024
	s_add_u32 s98, s20, 0x1800000
	s_addc_u32 s99, s21, 0
	global_load_dwordx4 v[72:75], v0, s[98:99] offset:3072
	global_load_dwordx4 v[108:111], v4, s[98:99]
	global_load_dwordx4 v[144:147], v4, s[98:99] offset:1024
	s_add_u32 s98, s20, 0x1c00000
	s_addc_u32 s99, s21, 0
	global_load_dwordx4 v[76:79], v0, s[98:99] offset:3072
	global_load_dwordx4 v[112:115], v4, s[98:99]
	global_load_dwordx4 v[154:157], v4, s[98:99] offset:1024
	global_store_dwordx4 v0, v[166:169], s[18:19]
	v_cvt_pk_bf16_f32 v178, v166, v167
	v_cvt_pk_bf16_f32 v179, v168, v169
	global_store_dwordx2 v34, v[178:179], s[16:17]
	v_lshlrev_b32_e32 v180, 16, v178
	v_and_b32_e32 v181, 0xffff0000, v178
	v_lshlrev_b32_e32 v182, 16, v179
	v_and_b32_e32 v183, 0xffff0000, v179
	v_mul_f32_e32 v184, v180, v180
	v_fmac_f32_e32 v184, v181, v181
	v_fmac_f32_e32 v184, v182, v182
	v_fmac_f32_e32 v184, v183, v183
	v_add_f32_e32 v5, v5, v184
	global_store_dwordx4 v0, v[170:173], s[18:19] offset:1024
	v_cvt_pk_bf16_f32 v178, v170, v171
	v_cvt_pk_bf16_f32 v179, v172, v173
	global_store_dwordx2 v35, v[178:179], s[16:17]
	v_lshlrev_b32_e32 v180, 16, v178
	v_and_b32_e32 v181, 0xffff0000, v178
	v_lshlrev_b32_e32 v182, 16, v179
	v_and_b32_e32 v183, 0xffff0000, v179
	v_mul_f32_e32 v184, v180, v180
	v_fmac_f32_e32 v184, v181, v181
	v_fmac_f32_e32 v184, v182, v182
	v_fmac_f32_e32 v184, v183, v183
	v_add_f32_e32 v5, v5, v184
	global_store_dwordx4 v0, v[174:177], s[18:19] offset:2048
	v_cvt_pk_bf16_f32 v178, v174, v175
	v_cvt_pk_bf16_f32 v179, v176, v177
	global_store_dwordx2 v36, v[178:179], s[16:17]
	v_lshlrev_b32_e32 v180, 16, v178
	v_and_b32_e32 v181, 0xffff0000, v178
	v_lshlrev_b32_e32 v182, 16, v179
	v_and_b32_e32 v183, 0xffff0000, v179
	v_mul_f32_e32 v184, v180, v180
	v_fmac_f32_e32 v184, v181, v181
	v_fmac_f32_e32 v184, v182, v182
	v_fmac_f32_e32 v184, v183, v183
	v_add_f32_e32 v5, v5, v184
	s_waitcnt vmcnt(6)
	v_pk_add_f32 v[168:169], v[46:47], v[50:51]
	v_pk_add_f32 v[166:167], v[44:45], v[48:49]
	v_pk_add_f32 v[168:169], v[168:169], v[54:55]
	v_pk_add_f32 v[166:167], v[166:167], v[52:53]
	v_pk_add_f32 v[168:169], v[168:169], v[58:59]
	v_pk_add_f32 v[166:167], v[166:167], v[56:57]
	v_pk_add_f32 v[168:169], v[168:169], v[62:63]
	v_pk_add_f32 v[166:167], v[166:167], v[60:61]
	v_pk_add_f32 v[168:169], v[168:169], v[66:67]
	v_pk_add_f32 v[166:167], v[166:167], v[64:65]
	v_pk_add_f32 v[168:169], v[168:169], v[70:71]
	v_pk_add_f32 v[166:167], v[166:167], v[68:69]
	v_pk_add_f32 v[168:169], v[168:169], v[74:75]
	v_pk_add_f32 v[166:167], v[166:167], v[72:73]
	v_pk_add_f32 v[168:169], v[168:169], v[78:79]
	v_pk_add_f32 v[166:167], v[166:167], v[76:77]
	v_pk_add_f32 v[172:173], v[82:83], v[86:87]
	v_pk_add_f32 v[170:171], v[80:81], v[84:85]
	v_pk_add_f32 v[172:173], v[172:173], v[90:91]
	v_pk_add_f32 v[170:171], v[170:171], v[88:89]
	v_pk_add_f32 v[172:173], v[172:173], v[94:95]
	v_pk_add_f32 v[170:171], v[170:171], v[92:93]
	v_pk_add_f32 v[172:173], v[172:173], v[98:99]
	v_pk_add_f32 v[170:171], v[170:171], v[96:97]
	v_pk_add_f32 v[172:173], v[172:173], v[102:103]
	v_pk_add_f32 v[170:171], v[170:171], v[100:101]
	v_pk_add_f32 v[172:173], v[172:173], v[106:107]
	v_pk_add_f32 v[170:171], v[170:171], v[104:105]
	v_pk_add_f32 v[172:173], v[172:173], v[110:111]
	v_pk_add_f32 v[170:171], v[170:171], v[108:109]
	v_pk_add_f32 v[172:173], v[172:173], v[114:115]
	v_pk_add_f32 v[170:171], v[170:171], v[112:113]
	v_pk_add_f32 v[176:177], v[118:119], v[122:123]
	v_pk_add_f32 v[174:175], v[116:117], v[120:121]
	v_pk_add_f32 v[176:177], v[176:177], v[126:127]
	v_pk_add_f32 v[174:175], v[174:175], v[124:125]
	v_pk_add_f32 v[176:177], v[176:177], v[130:131]
	v_pk_add_f32 v[174:175], v[174:175], v[128:129]
	v_pk_add_f32 v[176:177], v[176:177], v[134:135]
	v_pk_add_f32 v[174:175], v[174:175], v[132:133]
	v_pk_add_f32 v[176:177], v[176:177], v[138:139]
	v_pk_add_f32 v[174:175], v[174:175], v[136:137]
	v_pk_add_f32 v[176:177], v[176:177], v[142:143]
	v_pk_add_f32 v[174:175], v[174:175], v[140:141]
	v_pk_add_f32 v[176:177], v[176:177], v[146:147]
	v_pk_add_f32 v[174:175], v[174:175], v[144:145]
	v_pk_add_f32 v[176:177], v[176:177], v[156:157]
	v_pk_add_f32 v[174:175], v[174:175], v[154:155]
	global_load_dwordx4 v[44:47], v4, s[22:23] offset:2048
	global_load_dwordx4 v[80:83], v4, s[22:23] offset:3072
	s_mov_b64 s[98:99], s[20:21]
	global_load_dwordx4 v[48:51], v4, s[98:99] offset:2048
	global_load_dwordx4 v[84:87], v4, s[98:99] offset:3072
	s_add_u32 s98, s20, 0x400000
	s_addc_u32 s99, s21, 0
	global_load_dwordx4 v[52:55], v4, s[98:99] offset:2048
	global_load_dwordx4 v[88:91], v4, s[98:99] offset:3072
; DI unsigned pk2(float lo, float hi) { f32x2_t v = {lo, hi}; bf16x2_t b = __builtin_convertvector(v, bf16x2_t); return __builtin_bit_cast(unsigned, b); }
; DI void p10_hn(const Args& a, int lane, int wave) {
;     ...
;             for (int i = 0; i < 8; ++i) { v[i] = ((const f32x4*)xr)[lane + 64 * i];
; #pragma unroll
;                 for (int k = 0; k < 8; ++k) v[i] += ((const f32x4*)(pr + (size_t)k * (MS * 2048)))[lane + 64 * i];
;                 ((f32x4*)(a.out + (size_t)row * 2048))[lane + 64 * i] = v[i];
;                 u32x2 w; w.x = pk2(v[i][0], v[i][1]); w.y = pk2(v[i][2], v[i][3]);
;                 *(u32x2*)(H16 + (size_t)row * 2048 + 4 * (lane + 64 * i)) = w;
;                 const float b0 = bflo(w.x), b1 = bfhi(w.x), b2 = bflo(w.y), b3 = bfhi(w.y);
;                 ss += b0 * b0 + b1 * b1 + b2 * b2 + b3 * b3; }
;         }
;         ss = wave_sum(ss);
;         if (lane == 0) rs2[row] = 1.0f / (ss * (1.0f / 2048.0f) + EPS);
	s_add_u32 s98, s20, 0x800000
	s_addc_u32 s99, s21, 0
	global_load_dwordx4 v[56:59], v4, s[98:99] offset:2048
	global_load_dwordx4 v[92:95], v4, s[98:99] offset:3072
	s_add_u32 s98, s20, 0xc00000
	s_addc_u32 s99, s21, 0
	global_load_dwordx4 v[60:63], v4, s[98:99] offset:2048
	global_load_dwordx4 v[96:99], v4, s[98:99] offset:3072
	s_add_u32 s98, s20, 0x1000000
	s_addc_u32 s99, s21, 0
	global_load_dwordx4 v[64:67], v4, s[98:99] offset:2048
	global_load_dwordx4 v[100:103], v4, s[98:99] offset:3072
	s_add_u32 s98, s20, 0x1400000
	s_addc_u32 s99, s21, 0
	global_load_dwordx4 v[68:71], v4, s[98:99] offset:2048
	global_load_dwordx4 v[104:107], v4, s[98:99] offset:3072
	s_add_u32 s98, s20, 0x1800000
	s_addc_u32 s99, s21, 0
	global_load_dwordx4 v[72:75], v4, s[98:99] offset:2048
	global_load_dwordx4 v[108:111], v4, s[98:99] offset:3072
	s_add_u32 s98, s20, 0x1c00000
	s_addc_u32 s99, s21, 0
	global_load_dwordx4 v[76:79], v4, s[98:99] offset:2048
	global_load_dwordx4 v[112:115], v4, s[98:99] offset:3072
	global_store_dwordx4 v0, v[166:169], s[18:19] offset:3072
	v_cvt_pk_bf16_f32 v178, v166, v167
	v_cvt_pk_bf16_f32 v179, v168, v169
	global_store_dwordx2 v37, v[178:179], s[16:17]
	v_lshlrev_b32_e32 v180, 16, v178
	v_and_b32_e32 v181, 0xffff0000, v178
	v_lshlrev_b32_e32 v182, 16, v179
	v_and_b32_e32 v183, 0xffff0000, v179
	v_mul_f32_e32 v184, v180, v180
	v_fmac_f32_e32 v184, v181, v181
	v_fmac_f32_e32 v184, v182, v182
	v_fmac_f32_e32 v184, v183, v183
	v_add_f32_e32 v5, v5, v184
	global_store_dwordx4 v4, v[170:173], s[18:19]
	v_cvt_pk_bf16_f32 v178, v170, v171
	v_cvt_pk_bf16_f32 v179, v172, v173
	global_store_dwordx2 v38, v[178:179], s[16:17]
	v_lshlrev_b32_e32 v180, 16, v178
	v_and_b32_e32 v181, 0xffff0000, v178
	v_lshlrev_b32_e32 v182, 16, v179
	v_and_b32_e32 v183, 0xffff0000, v179
	v_mul_f32_e32 v184, v180, v180
	v_fmac_f32_e32 v184, v181, v181
	v_fmac_f32_e32 v184, v182, v182
	v_fmac_f32_e32 v184, v183, v183
	v_add_f32_e32 v5, v5, v184
	global_store_dwordx4 v4, v[174:177], s[18:19] offset:1024
	v_cvt_pk_bf16_f32 v178, v174, v175
	v_cvt_pk_bf16_f32 v179, v176, v177
	global_store_dwordx2 v39, v[178:179], s[16:17]
	v_lshlrev_b32_e32 v180, 16, v178
	v_and_b32_e32 v181, 0xffff0000, v178
	v_lshlrev_b32_e32 v182, 16, v179
	v_and_b32_e32 v183, 0xffff0000, v179
	v_mul_f32_e32 v184, v180, v180
	v_fmac_f32_e32 v184, v181, v181
	v_fmac_f32_e32 v184, v182, v182
	v_fmac_f32_e32 v184, v183, v183
	v_add_f32_e32 v5, v5, v184
	s_waitcnt vmcnt(6)
	v_pk_add_f32 v[168:169], v[46:47], v[50:51]
	v_pk_add_f32 v[166:167], v[44:45], v[48:49]
	v_pk_add_f32 v[168:169], v[168:169], v[54:55]
	v_pk_add_f32 v[166:167], v[166:167], v[52:53]
	v_pk_add_f32 v[168:169], v[168:169], v[58:59]
	v_pk_add_f32 v[166:167], v[166:167], v[56:57]
	v_pk_add_f32 v[168:169], v[168:169], v[62:63]
	v_pk_add_f32 v[166:167], v[166:167], v[60:61]
	v_pk_add_f32 v[168:169], v[168:169], v[66:67]
	v_pk_add_f32 v[166:167], v[166:167], v[64:65]
	v_pk_add_f32 v[168:169], v[168:169], v[70:71]
	v_pk_add_f32 v[166:167], v[166:167], v[68:69]
	v_pk_add_f32 v[168:169], v[168:169], v[74:75]
	v_pk_add_f32 v[166:167], v[166:167], v[72:73]
	v_pk_add_f32 v[168:169], v[168:169], v[78:79]
	v_pk_add_f32 v[166:167], v[166:167], v[76:77]
	v_pk_add_f32 v[172:173], v[82:83], v[86:87]
	v_pk_add_f32 v[170:171], v[80:81], v[84:85]
	v_pk_add_f32 v[172:173], v[172:173], v[90:91]
	v_pk_add_f32 v[170:171], v[170:171], v[88:89]
	v_pk_add_f32 v[172:173], v[172:173], v[94:95]
	v_pk_add_f32 v[170:171], v[170:171], v[92:93]
	v_pk_add_f32 v[172:173], v[172:173], v[98:99]
	v_pk_add_f32 v[170:171], v[170:171], v[96:97]
	v_pk_add_f32 v[172:173], v[172:173], v[102:103]
	v_pk_add_f32 v[170:171], v[170:171], v[100:101]
	v_pk_add_f32 v[172:173], v[172:173], v[106:107]
	v_pk_add_f32 v[170:171], v[170:171], v[104:105]
	v_pk_add_f32 v[172:173], v[172:173], v[110:111]
	v_pk_add_f32 v[170:171], v[170:171], v[108:109]
	v_pk_add_f32 v[172:173], v[172:173], v[114:115]
	v_pk_add_f32 v[170:171], v[170:171], v[112:113]
	global_store_dwordx4 v4, v[166:169], s[18:19] offset:2048
	v_cvt_pk_bf16_f32 v178, v166, v167
	v_cvt_pk_bf16_f32 v179, v168, v169
	global_store_dwordx2 v40, v[178:179], s[16:17]
	v_lshlrev_b32_e32 v180, 16, v178
	v_and_b32_e32 v181, 0xffff0000, v178
	v_lshlrev_b32_e32 v182, 16, v179
	v_and_b32_e32 v183, 0xffff0000, v179
	v_mul_f32_e32 v184, v180, v180
	v_fmac_f32_e32 v184, v181, v181
	v_fmac_f32_e32 v184, v182, v182
	v_fmac_f32_e32 v184, v183, v183
	v_add_f32_e32 v5, v5, v184
	global_store_dwordx4 v4, v[170:173], s[18:19] offset:3072
	v_cvt_pk_bf16_f32 v178, v170, v171
	v_cvt_pk_bf16_f32 v179, v172, v173
	global_store_dwordx2 v41, v[178:179], s[16:17]
	v_lshlrev_b32_e32 v180, 16, v178
	v_and_b32_e32 v181, 0xffff0000, v178
	v_lshlrev_b32_e32 v182, 16, v179
	v_and_b32_e32 v183, 0xffff0000, v179
	v_mul_f32_e32 v184, v180, v180
	v_fmac_f32_e32 v184, v181, v181
	v_fmac_f32_e32 v184, v182, v182
	v_fmac_f32_e32 v184, v183, v183
	v_add_f32_e32 v5, v5, v184
	s_mov_b64 s[16:17], 0
